# static s_setprio 1 for waves 0-3 (leading half) before each GEMM K-loop, per-segment flips removed, aligned loop heads
# speedup vs baseline: 1.0235x; 1.0235x over previous
; template <class Epi, class Sched>
; __device__ __forceinline__ void gemm_phase(LAS unsigned char* lds, const Gemm g, const Sched& S, const Epi& E) {
;     ...
;         const char* nA = has_next ? (const char*)g.A + (size_t)nxt.pm * tstep + nko : cA; const char* nB = has_next ? (const char*)g.Bt + (size_t)nxt.pn * tstep + nko : cB;
;     ...
;         for (int a = 0; a < 2; ++a)
; #pragma unroll
;             for (int b = 0; b < 2; ++b)
; #pragma unroll
;                 for (int m = 0; m < 4; ++m)
; #pragma unroll
;                     for (int n = 0; n < 2; ++n) acc[a][b][m][n] = (f32x4){0.f, 0.f, 0.f, 0.f};
.LBB0_502:
	s_ashr_i32 s51, s50, 31
	s_lshl_b64 s[12:13], s[50:51], 19
	s_add_u32 s54, s92, s12
	s_addc_u32 s55, s93, s13
	s_and_b64 s[12:13], s[38:39], exec
	s_cselect_b32 s7, s55, s15
	s_cselect_b32 s8, s54, s14
	s_ashr_i32 s53, s52, 31
	s_lshl_b64 s[12:13], s[52:53], 19
	s_add_u32 s56, s24, s12
	s_addc_u32 s57, s25, s13
	s_and_b64 s[12:13], s[38:39], exec
	s_cselect_b32 s12, s57, s17
	s_cselect_b32 s13, s56, s16
	s_add_u32 s14, s14, 0x40080
	s_addc_u32 s15, s15, 0
	s_add_u32 s21, s16, 0x100
	v_mov_b32_e32 v0, 0
	s_addc_u32 s33, s17, 0
	s_mov_b32 s40, -2
	v_mov_b32_e32 v1, v0
	s_waitcnt lgkmcnt(0)
	v_mov_b32_e32 v2, v0
	v_mov_b32_e32 v3, v0
	v_mov_b32_e32 v4, v0
	v_mov_b32_e32 v5, v0
	v_mov_b32_e32 v6, v0
	v_mov_b32_e32 v7, v0
	v_mov_b32_e32 v16, v0
	v_mov_b32_e32 v17, v0
	v_mov_b32_e32 v18, v0
	v_mov_b32_e32 v19, v0
	v_mov_b32_e32 v20, v0
	v_mov_b32_e32 v21, v0
	v_mov_b32_e32 v22, v0
	v_mov_b32_e32 v23, v0
	v_mov_b32_e32 v32, v0
	v_mov_b32_e32 v33, v0
	v_mov_b32_e32 v34, v0
	v_mov_b32_e32 v35, v0
	v_mov_b32_e32 v36, v0
	v_mov_b32_e32 v37, v0
	v_mov_b32_e32 v38, v0
	v_mov_b32_e32 v39, v0
	v_mov_b32_e32 v48, v0
	v_mov_b32_e32 v49, v0
	v_mov_b32_e32 v50, v0
	v_mov_b32_e32 v51, v0
	v_mov_b32_e32 v52, v0
	v_mov_b32_e32 v53, v0
	v_mov_b32_e32 v54, v0
	v_mov_b32_e32 v55, v0
	v_mov_b32_e32 v8, v0
	v_mov_b32_e32 v9, v0
	v_mov_b32_e32 v10, v0
	v_mov_b32_e32 v11, v0
	v_mov_b32_e32 v12, v0
	v_mov_b32_e32 v13, v0
	v_mov_b32_e32 v14, v0
	v_mov_b32_e32 v15, v0
	v_mov_b32_e32 v24, v0
	v_mov_b32_e32 v25, v0
	v_mov_b32_e32 v26, v0
	v_mov_b32_e32 v27, v0
	v_mov_b32_e32 v28, v0
	v_mov_b32_e32 v29, v0
	v_mov_b32_e32 v30, v0
	v_mov_b32_e32 v31, v0
	v_mov_b32_e32 v40, v0
	v_mov_b32_e32 v41, v0
	v_mov_b32_e32 v42, v0
	v_mov_b32_e32 v43, v0
	v_mov_b32_e32 v44, v0
	v_mov_b32_e32 v45, v0
	v_mov_b32_e32 v46, v0
	v_mov_b32_e32 v47, v0
	v_mov_b32_e32 v56, v0
	v_mov_b32_e32 v57, v0
	v_mov_b32_e32 v58, v0
	v_mov_b32_e32 v59, v0
	v_mov_b32_e32 v60, v0
	v_mov_b32_e32 v61, v0
	v_mov_b32_e32 v62, v0
	v_mov_b32_e32 v63, v0
	v_mov_b32_e32 v64, v0
	v_mov_b32_e32 v65, v0
	v_mov_b32_e32 v66, v0
	v_mov_b32_e32 v67, v0
	v_mov_b32_e32 v68, v0
	v_mov_b32_e32 v69, v0
	v_mov_b32_e32 v70, v0
	v_mov_b32_e32 v71, v0
	v_mov_b32_e32 v96, v0
	v_mov_b32_e32 v97, v0
	v_mov_b32_e32 v98, v0
	v_mov_b32_e32 v99, v0
	v_mov_b32_e32 v100, v0
	v_mov_b32_e32 v101, v0
	v_mov_b32_e32 v102, v0
	v_mov_b32_e32 v103, v0
	v_mov_b32_e32 v112, v0
	v_mov_b32_e32 v113, v0
	v_mov_b32_e32 v114, v0
	v_mov_b32_e32 v115, v0
	v_mov_b32_e32 v116, v0
	v_mov_b32_e32 v117, v0
	v_mov_b32_e32 v118, v0
	v_mov_b32_e32 v119, v0
	v_mov_b32_e32 v128, v0
	v_mov_b32_e32 v129, v0
	v_mov_b32_e32 v130, v0
	v_mov_b32_e32 v131, v0
	v_mov_b32_e32 v132, v0
	v_mov_b32_e32 v133, v0
	v_mov_b32_e32 v134, v0
	v_mov_b32_e32 v135, v0
	v_mov_b32_e32 v88, v0
	v_mov_b32_e32 v89, v0
	v_mov_b32_e32 v90, v0
	v_mov_b32_e32 v91, v0
	v_mov_b32_e32 v92, v0
	v_mov_b32_e32 v93, v0
	v_mov_b32_e32 v94, v0
	v_mov_b32_e32 v95, v0
	v_mov_b32_e32 v104, v0
	v_mov_b32_e32 v105, v0
	v_mov_b32_e32 v106, v0
	v_mov_b32_e32 v107, v0
	v_mov_b32_e32 v108, v0
	v_mov_b32_e32 v109, v0
	v_mov_b32_e32 v110, v0
	v_mov_b32_e32 v111, v0
	v_mov_b32_e32 v120, v0
	v_mov_b32_e32 v121, v0
	v_mov_b32_e32 v122, v0
	v_mov_b32_e32 v123, v0
	v_mov_b32_e32 v124, v0
	v_mov_b32_e32 v125, v0
	v_mov_b32_e32 v126, v0
	v_mov_b32_e32 v127, v0
	v_mov_b32_e32 v136, v0
	v_mov_b32_e32 v137, v0
	v_mov_b32_e32 v138, v0
	v_mov_b32_e32 v139, v0
	v_mov_b32_e32 v140, v0
	v_mov_b32_e32 v141, v0
	v_mov_b32_e32 v142, v0
	v_mov_b32_e32 v143, v0
	s_cmp_eq_u32 s48, 0
	s_cbranch_scc1 .Lprio503_skip
	s_setprio 1

; template <class Epi, class Sched>
; __device__ __forceinline__ void gemm_phase(LAS unsigned char* lds, const Gemm g, const Sched& S, const Epi& E) {
;     ...
;         const int nt = cur.kc >= 0 ? nts : ntf;
;         for (int t = 0; t < nt; t += 2) {
;     ...
;         for (int a = 0; a < 2; ++a)
; #pragma unroll
;             for (int b = 0; b < 2; ++b)
; #pragma unroll
;                 for (int m = 0; m < 4; ++m)
; #pragma unroll
;                     for (int n = 0; n < 2; ++n) acc[a][b][m][n] = (f32x4){0.f, 0.f, 0.f, 0.f};
.LBB0_598:
	s_cmp_lt_i32 s78, 0
	s_cselect_b32 s8, s22, s23
	s_add_i32 s12, s8, -2
	s_add_u32 s6, s6, 0x80
	s_addc_u32 s7, s7, 0
	s_add_u32 s13, s14, 0x100
	v_mov_b32_e32 v0, 0
	s_mov_b32 s17, 0
	s_addc_u32 s16, s15, 0
	v_mov_b32_e32 v1, v0
	v_mov_b32_e32 v2, v0
	v_mov_b32_e32 v3, v0
	v_mov_b32_e32 v4, v0
	v_mov_b32_e32 v5, v0
	v_mov_b32_e32 v6, v0
	v_mov_b32_e32 v7, v0
	v_mov_b32_e32 v8, v0
	v_mov_b32_e32 v9, v0
	v_mov_b32_e32 v10, v0
	v_mov_b32_e32 v11, v0
	v_mov_b32_e32 v12, v0
	v_mov_b32_e32 v13, v0
	v_mov_b32_e32 v14, v0
	v_mov_b32_e32 v15, v0
	v_mov_b32_e32 v24, v0
	v_mov_b32_e32 v25, v0
	v_mov_b32_e32 v26, v0
	v_mov_b32_e32 v27, v0
	v_mov_b32_e32 v28, v0
	v_mov_b32_e32 v29, v0
	v_mov_b32_e32 v30, v0
	v_mov_b32_e32 v31, v0
	v_mov_b32_e32 v40, v0
	v_mov_b32_e32 v41, v0
	v_mov_b32_e32 v42, v0
	v_mov_b32_e32 v43, v0
	v_mov_b32_e32 v44, v0
	v_mov_b32_e32 v45, v0
	v_mov_b32_e32 v46, v0
	v_mov_b32_e32 v47, v0
	v_mov_b32_e32 v16, v0
	v_mov_b32_e32 v17, v0
	v_mov_b32_e32 v18, v0
	v_mov_b32_e32 v19, v0
	v_mov_b32_e32 v20, v0
	v_mov_b32_e32 v21, v0
	v_mov_b32_e32 v22, v0
	v_mov_b32_e32 v23, v0
	v_mov_b32_e32 v32, v0
	v_mov_b32_e32 v33, v0
	v_mov_b32_e32 v34, v0
	v_mov_b32_e32 v35, v0
	v_mov_b32_e32 v36, v0
	v_mov_b32_e32 v37, v0
	v_mov_b32_e32 v38, v0
	v_mov_b32_e32 v39, v0
	v_mov_b32_e32 v48, v0
	v_mov_b32_e32 v49, v0
	v_mov_b32_e32 v50, v0
	v_mov_b32_e32 v51, v0
	v_mov_b32_e32 v52, v0
	v_mov_b32_e32 v53, v0
	v_mov_b32_e32 v54, v0
	v_mov_b32_e32 v55, v0
	v_mov_b32_e32 v56, v0
	v_mov_b32_e32 v57, v0
	v_mov_b32_e32 v58, v0
	v_mov_b32_e32 v59, v0
	v_mov_b32_e32 v60, v0
	v_mov_b32_e32 v61, v0
	v_mov_b32_e32 v62, v0
	v_mov_b32_e32 v63, v0
	v_mov_b32_e32 v64, v0
	v_mov_b32_e32 v65, v0
	v_mov_b32_e32 v66, v0
	v_mov_b32_e32 v67, v0
	v_mov_b32_e32 v68, v0
	v_mov_b32_e32 v69, v0
	v_mov_b32_e32 v70, v0
	v_mov_b32_e32 v71, v0
	v_mov_b32_e32 v72, v0
	v_mov_b32_e32 v73, v0
	v_mov_b32_e32 v74, v0
	v_mov_b32_e32 v75, v0
	v_mov_b32_e32 v76, v0
	v_mov_b32_e32 v77, v0
	v_mov_b32_e32 v78, v0
	v_mov_b32_e32 v79, v0
	v_mov_b32_e32 v84, v0
	v_mov_b32_e32 v85, v0
	v_mov_b32_e32 v86, v0
	v_mov_b32_e32 v87, v0
	v_mov_b32_e32 v92, v0
	v_mov_b32_e32 v93, v0
	v_mov_b32_e32 v94, v0
	v_mov_b32_e32 v95, v0
	v_mov_b32_e32 v100, v0
	v_mov_b32_e32 v101, v0
	v_mov_b32_e32 v102, v0
	v_mov_b32_e32 v103, v0
	v_mov_b32_e32 v108, v0
	v_mov_b32_e32 v109, v0
	v_mov_b32_e32 v110, v0
	v_mov_b32_e32 v111, v0
	v_mov_b32_e32 v80, v0
	v_mov_b32_e32 v81, v0
	v_mov_b32_e32 v82, v0
	v_mov_b32_e32 v83, v0
	v_mov_b32_e32 v88, v0
	v_mov_b32_e32 v89, v0
	v_mov_b32_e32 v90, v0
	v_mov_b32_e32 v91, v0
	v_mov_b32_e32 v96, v0
	v_mov_b32_e32 v97, v0
	v_mov_b32_e32 v98, v0
	v_mov_b32_e32 v99, v0
	v_mov_b32_e32 v104, v0
	v_mov_b32_e32 v105, v0
	v_mov_b32_e32 v106, v0
	v_mov_b32_e32 v107, v0
	v_mov_b32_e32 v112, v0
	v_mov_b32_e32 v113, v0
	v_mov_b32_e32 v114, v0
	v_mov_b32_e32 v115, v0
	v_mov_b32_e32 v116, v0
	v_mov_b32_e32 v117, v0
	v_mov_b32_e32 v118, v0
	v_mov_b32_e32 v119, v0
	v_mov_b32_e32 v120, v0
	v_mov_b32_e32 v121, v0
	v_mov_b32_e32 v122, v0
	v_mov_b32_e32 v123, v0
	v_mov_b32_e32 v124, v0
	v_mov_b32_e32 v125, v0
	v_mov_b32_e32 v126, v0
	v_mov_b32_e32 v127, v0
	s_cmp_eq_u32 s62, 0
	s_cbranch_scc1 .Lprio599_skip
	s_setprio 1

; template <class Epi, class Sched>
; __device__ __forceinline__ void gemm_phase(LAS unsigned char* lds, const Gemm g, const Sched& S, const Epi& E) {
;     ...
;         const char* nA = has_next ? (const char*)g.A + (size_t)nxt.pm * tstep + nko : cA; const char* nB = has_next ? (const char*)g.Bt + (size_t)nxt.pn * tstep + nko : cB;
;     ...
;         for (int a = 0; a < 2; ++a)
; #pragma unroll
;             for (int b = 0; b < 2; ++b)
; #pragma unroll
;                 for (int m = 0; m < 4; ++m)
; #pragma unroll
;                     for (int n = 0; n < 2; ++n) acc[a][b][m][n] = (f32x4){0.f, 0.f, 0.f, 0.f};
.LBB0_743:
	s_ashr_i32 s15, s14, 31
	s_lshl_b64 s[18:19], s[14:15], 19
	s_add_u32 s18, s92, s18
	s_addc_u32 s19, s93, s19
	s_and_b64 s[20:21], s[38:39], exec
	s_cselect_b32 s15, s19, s23
	s_cselect_b32 s44, s18, s22
	s_ashr_i32 s17, s16, 31
	s_lshl_b64 s[20:21], s[16:17], 19
	s_add_u32 s20, s9, s20
	s_addc_u32 s21, s12, s21
	s_and_b64 s[26:27], s[38:39], exec
	s_cselect_b32 s17, s21, s25
	s_cselect_b32 s45, s20, s24
	s_add_u32 s22, s22, 0x40080
	s_addc_u32 s23, s23, 0
	s_add_u32 s46, s24, 0x100
	v_mov_b32_e32 v4, 0
	s_addc_u32 s47, s25, 0
	s_mov_b32 s48, -2
	v_mov_b32_e32 v5, v4
	v_mov_b32_e32 v6, v4
	v_mov_b32_e32 v7, v4
	v_mov_b32_e32 v0, v4
	v_mov_b32_e32 v1, v4
	v_mov_b32_e32 v2, v4
	v_mov_b32_e32 v3, v4
	v_mov_b32_e32 v20, v4
	v_mov_b32_e32 v21, v4
	v_mov_b32_e32 v22, v4
	v_mov_b32_e32 v23, v4
	v_mov_b32_e32 v16, v4
	v_mov_b32_e32 v17, v4
	v_mov_b32_e32 v18, v4
	v_mov_b32_e32 v19, v4
	v_mov_b32_e32 v36, v4
	v_mov_b32_e32 v37, v4
	v_mov_b32_e32 v38, v4
	v_mov_b32_e32 v39, v4
	v_mov_b32_e32 v32, v4
	v_mov_b32_e32 v33, v4
	v_mov_b32_e32 v34, v4
	v_mov_b32_e32 v35, v4
	v_mov_b32_e32 v52, v4
	v_mov_b32_e32 v53, v4
	v_mov_b32_e32 v54, v4
	v_mov_b32_e32 v55, v4
	v_mov_b32_e32 v48, v4
	v_mov_b32_e32 v49, v4
	v_mov_b32_e32 v50, v4
	v_mov_b32_e32 v51, v4
	v_mov_b32_e32 v8, v4
	v_mov_b32_e32 v9, v4
	v_mov_b32_e32 v10, v4
	v_mov_b32_e32 v11, v4
	v_mov_b32_e32 v12, v4
	v_mov_b32_e32 v13, v4
	v_mov_b32_e32 v14, v4
	v_mov_b32_e32 v15, v4
	v_mov_b32_e32 v24, v4
	v_mov_b32_e32 v25, v4
	v_mov_b32_e32 v26, v4
	v_mov_b32_e32 v27, v4
	v_mov_b32_e32 v28, v4
	v_mov_b32_e32 v29, v4
	v_mov_b32_e32 v30, v4
	v_mov_b32_e32 v31, v4
	v_mov_b32_e32 v40, v4
	v_mov_b32_e32 v41, v4
	v_mov_b32_e32 v42, v4
	v_mov_b32_e32 v43, v4
	v_mov_b32_e32 v44, v4
	v_mov_b32_e32 v45, v4
	v_mov_b32_e32 v46, v4
	v_mov_b32_e32 v47, v4
	v_mov_b32_e32 v56, v4
	v_mov_b32_e32 v57, v4
	v_mov_b32_e32 v58, v4
	v_mov_b32_e32 v59, v4
	v_mov_b32_e32 v60, v4
	v_mov_b32_e32 v61, v4
	v_mov_b32_e32 v62, v4
	v_mov_b32_e32 v63, v4
	v_mov_b32_e32 v68, v4
	v_mov_b32_e32 v69, v4
	v_mov_b32_e32 v70, v4
	v_mov_b32_e32 v71, v4
	v_mov_b32_e32 v64, v4
	v_mov_b32_e32 v65, v4
	v_mov_b32_e32 v66, v4
	v_mov_b32_e32 v67, v4
	v_mov_b32_e32 v84, v4
	v_mov_b32_e32 v85, v4
	v_mov_b32_e32 v86, v4
	v_mov_b32_e32 v87, v4
	v_mov_b32_e32 v80, v4
	v_mov_b32_e32 v81, v4
	v_mov_b32_e32 v82, v4
	v_mov_b32_e32 v83, v4
	v_mov_b32_e32 v100, v4
	v_mov_b32_e32 v101, v4
	v_mov_b32_e32 v102, v4
	v_mov_b32_e32 v103, v4
	v_mov_b32_e32 v96, v4
	v_mov_b32_e32 v97, v4
	v_mov_b32_e32 v98, v4
	v_mov_b32_e32 v99, v4
	v_mov_b32_e32 v116, v4
	v_mov_b32_e32 v117, v4
	v_mov_b32_e32 v118, v4
	v_mov_b32_e32 v119, v4
	v_mov_b32_e32 v112, v4
	v_mov_b32_e32 v113, v4
	v_mov_b32_e32 v114, v4
	v_mov_b32_e32 v115, v4
	v_mov_b32_e32 v72, v4
	v_mov_b32_e32 v73, v4
	v_mov_b32_e32 v74, v4
	v_mov_b32_e32 v75, v4
	v_mov_b32_e32 v76, v4
	v_mov_b32_e32 v77, v4
	v_mov_b32_e32 v78, v4
	v_mov_b32_e32 v79, v4
	v_mov_b32_e32 v88, v4
	v_mov_b32_e32 v89, v4
	v_mov_b32_e32 v90, v4
	v_mov_b32_e32 v91, v4
	v_mov_b32_e32 v92, v4
	v_mov_b32_e32 v93, v4
	v_mov_b32_e32 v94, v4
	v_mov_b32_e32 v95, v4
	v_mov_b32_e32 v104, v4
	v_mov_b32_e32 v105, v4
	v_mov_b32_e32 v106, v4
	v_mov_b32_e32 v107, v4
	v_mov_b32_e32 v108, v4
	v_mov_b32_e32 v109, v4
	v_mov_b32_e32 v110, v4
	v_mov_b32_e32 v111, v4
	v_mov_b32_e32 v120, v4
	v_mov_b32_e32 v121, v4
	v_mov_b32_e32 v122, v4
	v_mov_b32_e32 v123, v4
	v_mov_b32_e32 v124, v4
	v_mov_b32_e32 v125, v4
	v_mov_b32_e32 v126, v4
	v_mov_b32_e32 v127, v4
	s_cmp_eq_u32 s6, 0
	s_cbranch_scc1 .Lprio744_skip
	s_setprio 1
